# v36: v34 with the next V tile's LDS writes issued inside the PV segment (after the last V fragment read is issued) instead of after it
# speedup vs baseline: 1.0069x; 1.0026x over previous
.Lattn_common_a:
	v_mfma_f32_32x32x16_bf16 v[48:63], v[166:169], v[214:217], v[48:63]
	ds_read_b64_tr_b16 v[214:215], v186 offset:0x2200
	ds_read_b64_tr_b16 v[216:217], v186 offset:0x2a00
	v_fmamk_f32 v80, v80, 0x3e0293ee, v242
	v_fmamk_f32 v81, v81, 0x3e0293ee, v242
	v_fmamk_f32 v82, v82, 0x3e0293ee, v242
	v_fmamk_f32 v83, v83, 0x3e0293ee, v242
	s_waitcnt lgkmcnt(4)
	v_mfma_f32_32x32x16_bf16 v[32:47], v[166:169], v[218:221], v[32:47]
	ds_read_b64_tr_b16 v[218:219], v186 offset:0x2400
	ds_read_b64_tr_b16 v[220:221], v186 offset:0x2c00
	v_fmamk_f32 v84, v84, 0x3e0293ee, v242
	v_fmamk_f32 v85, v85, 0x3e0293ee, v242
	v_fmamk_f32 v86, v86, 0x3e0293ee, v242
	v_fmamk_f32 v87, v87, 0x3e0293ee, v242
	v_fmamk_f32 v88, v88, 0x3e0293ee, v242
	v_fmamk_f32 v89, v89, 0x3e0293ee, v242
	v_mfma_f32_32x32x16_bf16 v[16:31], v[166:169], v[222:225], v[16:31]
	ds_read_b64_tr_b16 v[222:223], v186 offset:0x2600
	ds_read_b64_tr_b16 v[224:225], v186 offset:0x2e00
	v_fmamk_f32 v90, v90, 0x3e0293ee, v242
	v_fmamk_f32 v91, v91, 0x3e0293ee, v242
	v_fmamk_f32 v92, v92, 0x3e0293ee, v242
	v_fmamk_f32 v93, v93, 0x3e0293ee, v242
	v_fmamk_f32 v94, v94, 0x3e0293ee, v242
	v_fmamk_f32 v95, v95, 0x3e0293ee, v242
	s_waitcnt lgkmcnt(4)
	v_mfma_f32_32x32x16_bf16 v[0:15], v[172:175], v[210:213], v[0:15]
	ds_read_b64_tr_b16 v[210:211], v186 offset:0x3000
	ds_read_b64_tr_b16 v[212:213], v186 offset:0x3800
	v_exp_f32_e32 v177, v81
	v_exp_f32_e32 v176, v83
	v_exp_f32_e32 v171, v93
	v_mfma_f32_32x32x16_bf16 v[48:63], v[172:175], v[214:217], v[48:63]
	ds_read_b64_tr_b16 v[214:215], v186 offset:0x3200
	ds_read_b64_tr_b16 v[216:217], v186 offset:0x3a00
	v_exp_f32_e32 v170, v95
	v_exp_f32_e32 v162, v80
	v_exp_f32_e32 v163, v82
	s_waitcnt lgkmcnt(4)
	v_mfma_f32_32x32x16_bf16 v[32:47], v[172:175], v[218:221], v[32:47]
	ds_read_b64_tr_b16 v[218:219], v186 offset:0x3400
	ds_read_b64_tr_b16 v[220:221], v186 offset:0x3c00
	v_exp_f32_e32 v164, v84
	v_exp_f32_e32 v165, v86
	v_exp_f32_e32 v166, v88
	v_mfma_f32_32x32x16_bf16 v[16:31], v[172:175], v[222:225], v[16:31]
	ds_read_b64_tr_b16 v[222:223], v186 offset:0x3600
	ds_read_b64_tr_b16 v[224:225], v186 offset:0x3e00
	v_exp_f32_e32 v167, v90
	v_exp_f32_e32 v168, v92
	v_exp_f32_e32 v169, v94
	s_waitcnt lgkmcnt(4)
	v_mfma_f32_32x32x16_bf16 v[0:15], v[206:209], v[210:213], v[0:15]
	v_exp_f32_e32 v175, v85
	v_exp_f32_e32 v174, v87
	v_exp_f32_e32 v173, v89
	v_mfma_f32_32x32x16_bf16 v[48:63], v[206:209], v[214:217], v[48:63]
	v_exp_f32_e32 v172, v91
	v_add_u32_e32 v248, s101, v190
	v_add_u32_e32 v249, s101, v191
	ds_write_b128 v248, v[130:133]
	ds_write_b128 v249, v[138:141]
	s_waitcnt lgkmcnt(2)
	v_mfma_f32_32x32x16_bf16 v[32:47], v[206:209], v[218:221], v[32:47]
	v_mfma_f32_32x32x16_bf16 v[16:31], v[206:209], v[222:225], v[16:31]
	v_cndmask_b32_e64 v206, v241, 1.0, s[42:43]
	s_cmp_lg_u64 s[42:43], 0
	s_cbranch_scc1 .LBB0_530
	s_and_saveexec_b64 s[6:7], s[40:41]
	ds_write_b32 v184, v206 offset:128
	s_or_b64 exec, exec, s[6:7]
	s_waitcnt lgkmcnt(0)
	ds_read_b128 v[210:213], v182 offset:224
	ds_read_b128 v[214:217], v182 offset:192
	ds_read_b128 v[218:221], v182 offset:160
	ds_read_b128 v[222:225], v182 offset:128
	s_waitcnt lgkmcnt(3)
	v_pk_mul_f32 v[14:15], v[14:15], v[212:213]
	s_waitcnt lgkmcnt(2)
	v_pk_mul_f32 v[10:11], v[10:11], v[216:217]
	s_waitcnt lgkmcnt(1)
	v_pk_mul_f32 v[6:7], v[6:7], v[220:221]
	s_waitcnt lgkmcnt(0)
	v_pk_mul_f32 v[2:3], v[2:3], v[224:225]
	v_pk_mul_f32 v[12:13], v[12:13], v[210:211]
	v_pk_mul_f32 v[8:9], v[8:9], v[214:215]
	v_pk_mul_f32 v[4:5], v[4:5], v[218:219]
	v_pk_mul_f32 v[0:1], v[0:1], v[222:223]
	v_pk_mul_f32 v[62:63], v[62:63], v[212:213]
	v_pk_mul_f32 v[58:59], v[58:59], v[216:217]
	v_pk_mul_f32 v[54:55], v[54:55], v[220:221]
	v_pk_mul_f32 v[50:51], v[50:51], v[224:225]
	v_pk_mul_f32 v[60:61], v[60:61], v[210:211]
	v_pk_mul_f32 v[56:57], v[56:57], v[214:215]
	v_pk_mul_f32 v[52:53], v[52:53], v[218:219]
	v_pk_mul_f32 v[48:49], v[48:49], v[222:223]
	v_pk_mul_f32 v[46:47], v[46:47], v[212:213]
	v_pk_mul_f32 v[42:43], v[42:43], v[216:217]
	v_pk_mul_f32 v[38:39], v[38:39], v[220:221]
	v_pk_mul_f32 v[34:35], v[34:35], v[224:225]
	v_pk_mul_f32 v[44:45], v[44:45], v[210:211]
	v_pk_mul_f32 v[40:41], v[40:41], v[214:215]
	v_pk_mul_f32 v[36:37], v[36:37], v[218:219]
	v_pk_mul_f32 v[32:33], v[32:33], v[222:223]
	v_pk_mul_f32 v[30:31], v[30:31], v[212:213]
	v_pk_mul_f32 v[26:27], v[26:27], v[216:217]
	v_pk_mul_f32 v[22:23], v[22:23], v[220:221]
	v_pk_mul_f32 v[18:19], v[18:19], v[224:225]
	v_pk_mul_f32 v[28:29], v[28:29], v[210:211]
	v_pk_mul_f32 v[24:25], v[24:25], v[214:215]
	v_pk_mul_f32 v[20:21], v[20:21], v[218:219]
	v_pk_mul_f32 v[16:17], v[16:17], v[222:223]

.Lattn_common_b:
	v_mfma_f32_32x32x16_bf16 v[48:63], v[166:169], v[214:217], v[48:63]
	ds_read_b64_tr_b16 v[214:215], v186 offset:0x2200
	ds_read_b64_tr_b16 v[216:217], v186 offset:0x2a00
	v_fmamk_f32 v80, v80, 0x3e0293ee, v242
	v_fmamk_f32 v81, v81, 0x3e0293ee, v242
	v_fmamk_f32 v82, v82, 0x3e0293ee, v242
	v_fmamk_f32 v83, v83, 0x3e0293ee, v242
	s_waitcnt lgkmcnt(4)
	v_mfma_f32_32x32x16_bf16 v[32:47], v[166:169], v[218:221], v[32:47]
	ds_read_b64_tr_b16 v[218:219], v186 offset:0x2400
	ds_read_b64_tr_b16 v[220:221], v186 offset:0x2c00
	v_fmamk_f32 v84, v84, 0x3e0293ee, v242
	v_fmamk_f32 v85, v85, 0x3e0293ee, v242
	v_fmamk_f32 v86, v86, 0x3e0293ee, v242
	v_fmamk_f32 v87, v87, 0x3e0293ee, v242
	v_fmamk_f32 v88, v88, 0x3e0293ee, v242
	v_fmamk_f32 v89, v89, 0x3e0293ee, v242
	v_mfma_f32_32x32x16_bf16 v[16:31], v[166:169], v[222:225], v[16:31]
	ds_read_b64_tr_b16 v[222:223], v186 offset:0x2600
	ds_read_b64_tr_b16 v[224:225], v186 offset:0x2e00
	v_fmamk_f32 v90, v90, 0x3e0293ee, v242
	v_fmamk_f32 v91, v91, 0x3e0293ee, v242
	v_fmamk_f32 v92, v92, 0x3e0293ee, v242
	v_fmamk_f32 v93, v93, 0x3e0293ee, v242
	v_fmamk_f32 v94, v94, 0x3e0293ee, v242
	v_fmamk_f32 v95, v95, 0x3e0293ee, v242
	s_waitcnt lgkmcnt(4)
	v_mfma_f32_32x32x16_bf16 v[0:15], v[170:173], v[210:213], v[0:15]
	ds_read_b64_tr_b16 v[210:211], v186 offset:0x3000
	ds_read_b64_tr_b16 v[212:213], v186 offset:0x3800
	v_exp_f32_e32 v207, v83
	v_exp_f32_e32 v163, v80
	v_exp_f32_e32 v164, v82
	v_mfma_f32_32x32x16_bf16 v[48:63], v[170:173], v[214:217], v[48:63]
	ds_read_b64_tr_b16 v[214:215], v186 offset:0x3200
	ds_read_b64_tr_b16 v[216:217], v186 offset:0x3a00
	v_exp_f32_e32 v165, v86
	v_exp_f32_e32 v166, v88
	v_exp_f32_e32 v167, v90
	s_waitcnt lgkmcnt(4)
	v_mfma_f32_32x32x16_bf16 v[32:47], v[170:173], v[218:221], v[32:47]
	ds_read_b64_tr_b16 v[218:219], v186 offset:0x3400
	ds_read_b64_tr_b16 v[220:221], v186 offset:0x3c00
	v_exp_f32_e32 v168, v92
	v_exp_f32_e32 v169, v94
	v_mfma_f32_32x32x16_bf16 v[16:31], v[170:173], v[222:225], v[16:31]
	ds_read_b64_tr_b16 v[222:223], v186 offset:0x3600
	ds_read_b64_tr_b16 v[224:225], v186 offset:0x3e00
	s_waitcnt lgkmcnt(4)
	v_mfma_f32_32x32x16_bf16 v[0:15], v[174:177], v[210:213], v[0:15]
	v_exp_f32_e32 v171, v93
	v_exp_f32_e32 v172, v95
	v_exp_f32_e32 v173, v89
	v_mfma_f32_32x32x16_bf16 v[48:63], v[174:177], v[214:217], v[48:63]
	v_exp_f32_e32 v210, v85
	v_add_u32_e32 v248, s100, v190
	v_add_u32_e32 v249, s100, v191
	ds_write_b128 v248, v[146:149]
	ds_write_b128 v249, v[150:153]
	s_waitcnt lgkmcnt(2)
	v_mfma_f32_32x32x16_bf16 v[32:47], v[174:177], v[218:221], v[32:47]
	v_mfma_f32_32x32x16_bf16 v[16:31], v[174:177], v[222:225], v[16:31]
	v_exp_f32_e32 v174, v91
	v_exp_f32_e32 v175, v87
	v_exp_f32_e32 v176, v84
	v_exp_f32_e32 v177, v81
	v_cndmask_b32_e64 v162, v241, 1.0, s[42:43]
	s_cmp_lg_u64 s[42:43], 0
	s_cbranch_scc1 .LBB0_536
	s_and_saveexec_b64 s[8:9], s[40:41]
	ds_write_b32 v184, v162 offset:128
	s_or_b64 exec, exec, s[8:9]
	s_waitcnt lgkmcnt(0)
	ds_read_b128 v[146:149], v182 offset:224
	ds_read_b128 v[150:153], v182 offset:192
	ds_read_b128 v[154:157], v182 offset:160
	ds_read_b128 v[158:161], v182 offset:128
	s_waitcnt lgkmcnt(3)
	v_pk_mul_f32 v[14:15], v[14:15], v[148:149]
	s_waitcnt lgkmcnt(2)
	v_pk_mul_f32 v[10:11], v[10:11], v[152:153]
	s_waitcnt lgkmcnt(1)
	v_pk_mul_f32 v[6:7], v[6:7], v[156:157]
	s_waitcnt lgkmcnt(0)
	v_pk_mul_f32 v[2:3], v[2:3], v[160:161]
	v_pk_mul_f32 v[12:13], v[12:13], v[146:147]
	v_pk_mul_f32 v[8:9], v[8:9], v[150:151]
	v_pk_mul_f32 v[4:5], v[4:5], v[154:155]
	v_pk_mul_f32 v[0:1], v[0:1], v[158:159]
	v_pk_mul_f32 v[62:63], v[62:63], v[148:149]
	v_pk_mul_f32 v[58:59], v[58:59], v[152:153]
	v_pk_mul_f32 v[54:55], v[54:55], v[156:157]
	v_pk_mul_f32 v[50:51], v[50:51], v[160:161]
	v_pk_mul_f32 v[60:61], v[60:61], v[146:147]
	v_pk_mul_f32 v[56:57], v[56:57], v[150:151]
	v_pk_mul_f32 v[52:53], v[52:53], v[154:155]
	v_pk_mul_f32 v[48:49], v[48:49], v[158:159]
	v_pk_mul_f32 v[46:47], v[46:47], v[148:149]
	v_pk_mul_f32 v[42:43], v[42:43], v[152:153]
	v_pk_mul_f32 v[38:39], v[38:39], v[156:157]
	v_pk_mul_f32 v[34:35], v[34:35], v[160:161]
	v_pk_mul_f32 v[44:45], v[44:45], v[146:147]
	v_pk_mul_f32 v[40:41], v[40:41], v[150:151]
	v_pk_mul_f32 v[36:37], v[36:37], v[154:155]
	v_pk_mul_f32 v[32:33], v[32:33], v[158:159]
	v_pk_mul_f32 v[30:31], v[30:31], v[148:149]
	v_pk_mul_f32 v[26:27], v[26:27], v[152:153]
	v_pk_mul_f32 v[22:23], v[22:23], v[156:157]
	v_pk_mul_f32 v[18:19], v[18:19], v[160:161]
	v_pk_mul_f32 v[28:29], v[28:29], v[146:147]
	v_pk_mul_f32 v[24:25], v[24:25], v[150:151]
	v_pk_mul_f32 v[20:21], v[20:21], v[154:155]
	v_pk_mul_f32 v[16:17], v[16:17], v[158:159]
